# P3 units assigned by XCD-contiguous index (the 8 segments of a (b,h) on one XCD) so P3a|P3b is also an XCD-local barrier; placement check moved to the first two barriers
# speedup vs baseline: 1.0118x; 1.0039x over previous
; __device__ __forceinline__ float wave_sum(float v) {
; #pragma unroll
;     for (int o = 1; o < 64; o <<= 1) v += __shfl_xor(v, o);
;     return v;
; __device__ __forceinline__ void norm_phase(const float* X, const float* __restrict__ gain, const float* mod, int sh_off, int sc_off, bf16_t* H, int gw, int NGW, int lane) {
;     for (int rg = gw; rg < M / 8; rg += NGW) {
;         const int row0 = rg * 8, b = row0 >> 12;
;         f32x4 gs[8], sh[8];
; #pragma unroll
;         for (int j = 0; j < 8; ++j) { const f32x4 g = ((const f32x4*)gain)[lane + 64 * j]; const f32x4 s = ((const f32x4*)(mod + (size_t)b * NMOD + sc_off))[lane + 64 * j];
;             gs[j] = g * (s + 1.0f); sh[j] = ((const f32x4*)(mod + (size_t)b * NMOD + sh_off))[lane + 64 * j]; }
.LBB0_131:
	s_or_b64 exec, exec, s[0:1]
	v_readlane_b32 s98, v236, 2
	v_readlane_b32 s99, v236, 3
	v_add_u32_e32 v239, 8, v237
	v_and_b32_e32 v239, 0xff, v239
	v_lshrrev_b32_e32 v238, 5, v239
	v_and_b32_e32 v239, 31, v239
	v_lshlrev_b32_e32 v238, 8, v238
	v_lshl_add_u32 v238, v239, 2, v238
	v_add_u32_e32 v238, 0x404, v238
	global_load_dword v238, v238, s[98:99] sc0 sc1
	s_cmpk_lt_i32 s50, 0x800
	s_cselect_b64 s[0:1], -1, 0
	v_writelane_b32 v236, s0, 48
	s_cmpk_gt_i32 s50, 0x7ff
	s_waitcnt lgkmcnt(0)
	s_barrier
	v_writelane_b32 v236, s1, 49
	s_cbranch_scc1 .LBB0_136
	v_readlane_b32 s16, v236, 7
	v_readlane_b32 s17, v236, 8
	v_readlane_b32 s18, v236, 9
	v_readlane_b32 s19, v236, 10
	v_readlane_b32 s20, v236, 11
	v_readlane_b32 s21, v236, 12
	v_readlane_b32 s22, v236, 13
	v_readlane_b32 s23, v236, 14
	v_readlane_b32 s24, v236, 15
	v_readlane_b32 s25, v236, 16
	s_waitcnt vmcnt(15)
	v_lshlrev_b32_e32 v32, 4, v160
	v_readlane_b32 s26, v236, 17
	v_readlane_b32 s27, v236, 18
	v_readlane_b32 s28, v236, 19
	v_readlane_b32 s29, v236, 20
	v_readlane_b32 s30, v236, 21
	v_readlane_b32 s31, v236, 22
	s_mov_b64 s[8:9], s[16:17]
	s_mov_b64 s[16:17], s[24:25]
	global_load_dwordx4 v[0:3], v32, s[16:17]
	global_load_dwordx4 v[4:7], v32, s[16:17] offset:1024
	global_load_dwordx4 v[8:11], v32, s[16:17] offset:2048
	global_load_dwordx4 v[12:15], v32, s[16:17] offset:3072
	v_or_b32_e32 v34, 0x100, v160
	s_waitcnt vmcnt(18)
	v_or_b32_e32 v36, 0x140, v160
	v_or_b32_e32 v38, 0x180, v160
	s_waitcnt vmcnt(17)
	v_or_b32_e32 v40, 0x1c0, v160
	v_lshlrev_b32_e32 v16, 4, v34
	v_lshlrev_b32_e32 v20, 4, v36
	v_lshlrev_b32_e32 v24, 4, v38
	v_lshlrev_b32_e32 v28, 4, v40
	global_load_dwordx4 v[16:19], v16, s[16:17]
	s_nop 0
	global_load_dwordx4 v[20:23], v20, s[16:17]
	s_nop 0
	global_load_dwordx4 v[24:27], v24, s[16:17]
	s_nop 0
	global_load_dwordx4 v[28:31], v28, s[16:17]
	v_mbcnt_lo_u32_b32 v35, -1, 0
	v_mbcnt_hi_u32_b32 v35, -1, v35
	v_and_b32_e32 v37, 64, v35
	v_add_u32_e32 v37, 64, v37
	v_xor_b32_e32 v39, 1, v35
	v_cmp_lt_i32_e32 vcc, v39, v37
	v_mov_b32_e32 v33, 0
	s_waitcnt vmcnt(19)
	v_lshl_add_u64 v[48:49], s[8:9], 0, v[32:33]
	v_cndmask_b32_e32 v39, v35, v39, vcc
	v_lshlrev_b32_e32 v136, 2, v39
	v_xor_b32_e32 v39, 2, v35
	v_cmp_lt_i32_e32 vcc, v39, v37
	s_mov_b64 s[0:1], 0x1000
	v_lshl_add_u64 v[96:97], v[48:49], 0, s[0:1]
	v_cndmask_b32_e32 v39, v35, v39, vcc
	v_lshlrev_b32_e32 v137, 2, v39
	v_xor_b32_e32 v39, 4, v35
	v_cmp_lt_i32_e32 vcc, v39, v37
	v_readlane_b32 s0, v236, 0
	v_readlane_b32 s1, v236, 45
	v_cndmask_b32_e32 v39, v35, v39, vcc
	v_lshlrev_b32_e32 v138, 2, v39
	v_xor_b32_e32 v39, 8, v35
	v_cmp_lt_i32_e32 vcc, v39, v37
	s_mov_b64 s[18:19], s[26:27]
	v_or_b32_e32 v42, 64, v160
	v_cndmask_b32_e32 v39, v35, v39, vcc
	v_lshlrev_b32_e32 v139, 2, v39
	v_xor_b32_e32 v39, 16, v35
	v_cmp_lt_i32_e32 vcc, v39, v37
	v_or_b32_e32 v44, 0x80, v160
	v_or_b32_e32 v46, 0xc0, v160
	v_cndmask_b32_e32 v39, v35, v39, vcc
	v_lshlrev_b32_e32 v140, 2, v39
	v_xor_b32_e32 v39, 32, v35
	v_cmp_lt_i32_e32 vcc, v39, v37
	s_lshl_b32 s0, s0, 6
	s_lshl_b32 s1, s1, 3
	v_cndmask_b32_e32 v35, v35, v39, vcc
	v_lshlrev_b32_e32 v32, 3, v160
	v_lshlrev_b32_e32 v141, 2, v35
	s_add_i32 s2, s0, s1
	s_lshl_b32 s16, s62, 6
	v_lshl_add_u64 v[98:99], s[60:61], 0, v[32:33]
	s_mov_b64 s[4:5], 0x2000
	v_lshlrev_b32_e32 v142, 4, v160
	v_lshlrev_b32_e32 v143, 4, v42
	v_lshlrev_b32_e32 v144, 4, v44
	v_lshlrev_b32_e32 v145, 4, v46
	v_lshlrev_b32_e32 v146, 4, v34
	v_lshlrev_b32_e32 v147, 4, v36
	v_lshlrev_b32_e32 v148, 4, v38
	v_lshlrev_b32_e32 v149, 4, v40
	v_mov_b32_e32 v150, 0x358637bd
	s_mov_b32 s17, 0xf800000
	v_mov_b32_e32 v151, 0x260
	s_mov_b32 s18, 0x7800000
	s_mov_b32 s19, s50
	s_mov_b64 s[20:21], s[28:29]
	s_mov_b64 s[22:23], s[30:31]

; #define LAS __attribute__((address_space(3)))
; __device__ __forceinline__ void swa_load(SwaRaw& R, int b, int kvh, int nb, const bf16_t* P, int tid) {
;     const size_t rq0 = (size_t)b * SEQ + (size_t)nb * 128; const int ch = tid & 7;
; #pragma unroll
;     for (int p = 0; p < 4; ++p) { const int ki = (tid >> 3) + 64 * p; const bool valid = (nb > 0) || (ki >= 128);
;         R.k[p] = (u32x4){0u, 0u, 0u, 0u}; R.v[p] = (u32x4){0u, 0u, 0u, 0u};
;         if (valid) { const size_t row = rq0 - 128 + ki; R.k[p] = *(const u32x4*)(P + row * PLD + 4096 + kvh * 64 + ch * 8); R.v[p] = *(const u32x4*)(P + row * PLD + 4352 + kvh * 64 + ch * 8); } }
; #pragma unroll
;     for (int p = 0; p < 2; ++p) R.q[p] = *(const u32x4*)(P + (rq0 + (tid >> 3) + 64 * p) * PLD + 3072 + (kvh * 4) * 64 + ch * 8);
; }
; __device__ __forceinline__ void swa_compute(SwaRaw& R, int b, int kvh, int nb, const bf16_t* P, const float* __restrict__ qg, const float* __restrict__ kg, const float* __restrict__ sinks, bf16_t* OB, LAS unsigned char* lds, int tid) {
;     const int lane = tid & 63, wid = __builtin_amdgcn_readfirstlane(tid >> 6), fr = lane & 15, fq = lane >> 4;
;     LAS bf16_t* Qs = (LAS bf16_t*)lds;
;     LAS bf16_t* Ks = Qs + 128 * 72;
;     LAS bf16_t* Vr = Ks + 256 * 72;
;     LAS bf16_t* Pw = Vr + 256 * 72 + wid * (16 * 168);
;     const size_t rq0 = (size_t)b * SEQ + (size_t)nb * 128;
;     const int ch = tid & 7;
; __global__ void __launch_bounds__(NTHR, 2) fwd_megakernel(Args a) {
;     ...
;     for (int u = blk; u < 256; u += G) { SwaRaw R; swa_load(R, u >> 7, (u >> 5) & 3, u & 31, P, tid);
;         hgrn_state(u >> 6, (u >> 3) & 7, u & 7, P, LOGF, SSEG, DSEG, lds, tid);
;         swa_compute(R, u >> 7, (u >> 5) & 3, u & 31, P, qg, kg, sinks, OAB, lds, tid); }
.LBB0_390:
	v_writelane_b32 v236, s56, 56
	v_writelane_b32 v235, s55, 0
	s_nop 0
	v_writelane_b32 v236, s57, 57
	v_writelane_b32 v236, s58, 58
	v_writelane_b32 v236, s59, 59
	v_writelane_b32 v236, s60, 60
	v_writelane_b32 v236, s61, 61
	v_writelane_b32 v236, s62, 62
	v_writelane_b32 v236, s63, 63
	s_or_b64 exec, exec, s[0:1]
	v_readlane_b32 s98, v236, 2
	v_readlane_b32 s99, v236, 3
	v_mov_b32_e32 v238, 0x100
	s_nop 4
	global_load_dword v238, v238, s[98:99] sc0 sc1
	s_waitcnt lgkmcnt(0)
	v_cndmask_b32_e64 v0, 0, 1, s[14:15]
	v_cmp_ne_u32_e64 s[0:1], 1, v0
	v_bfe_u32 v0, v186, 4, 2
	s_andn2_b64 vcc, exec, s[14:15]
	v_writelane_b32 v235, s0, 1
	v_bfe_u32 v185, v186, 2, 2
	v_lshrrev_b32_e32 v88, 3, v186
	v_writelane_b32 v235, s1, 2
	v_lshlrev_b32_e32 v188, 3, v186
	v_lshlrev_b32_e32 v96, 1, v160
	v_and_b32_e32 v91, 15, v186
	v_and_b32_e32 v90, 48, v186
	v_lshlrev_b32_e32 v92, 4, v186
	v_lshlrev_b32_e32 v94, 3, v0
	v_lshlrev_b32_e32 v161, 2, v0
	v_lshl_add_u32 v184, v0, 4, 0
	v_and_b32_e32 v97, 7, v186
	v_writelane_b32 v235, s72, 3
	s_barrier
	s_nop 0
	v_writelane_b32 v235, s73, 4
	s_cbranch_vccnz .LBB0_408
	s_movk_i32 s0, 0x1ff
	v_cmp_lt_u32_e64 s[0:1], s0, v186
	v_mov_b32_e32 v99, 0
	v_mov_b32_e32 v93, v99
	v_writelane_b32 v235, s0, 5
	v_lshlrev_b32_e32 v98, 3, v160
	v_and_b32_e32 v0, 56, v188
	v_writelane_b32 v235, s1, 6
	v_readlane_b32 s0, v236, 56
	v_readlane_b32 s6, v236, 62
	v_readlane_b32 s7, v236, 63
	v_readlane_b32 s4, v236, 60
	v_readlane_b32 s5, v236, 61
	s_mov_b64 s[10:11], s[6:7]
	v_readlane_b32 s2, v236, 58
	v_readlane_b32 s3, v236, 59
	s_mov_b64 s[8:9], s[4:5]
	s_mov_b64 s[6:7], s[2:3]
	v_lshl_add_u64 v[2:3], s[8:9], 0, v[92:93]
	s_mov_b64 s[2:3], 0x1c800000
	v_lshl_add_u64 v[108:109], v[2:3], 0, s[2:3]
	v_lshl_add_u64 v[2:3], s[8:9], 0, v[98:99]
	s_mov_b64 s[2:3], 0x1d800000
	s_add_i32 s0, 0, 0x11000
	v_lshl_add_u64 v[110:111], v[2:3], 0, s[2:3]
	v_readlane_b32 s12, v236, 23
	v_lshl_add_u32 v5, v0, 1, 0
	v_mul_u32_u24_e32 v2, 0x48, v88
	v_lshl_add_u64 v[106:107], s[6:7], 0, v[98:99]
	v_add_u32_e32 v189, s0, v98
	v_lshlrev_b32_e32 v98, 2, v0
	v_readlane_b32 s13, v236, 24
	v_readlane_b32 s14, v236, 25
	v_readlane_b32 s15, v236, 26
	v_lshl_add_u32 v93, v2, 1, v5
	v_mul_u32_u24_e32 v2, 0x150, v91
	s_add_i32 s0, 0, 0x16800
	v_and_b32_e32 v3, 24, v188
	v_mov_b32_e32 v95, v99
	v_readlane_b32 s1, v236, 57
	v_mul_u32_u24_e32 v1, 0x110, v160
	v_add_u32_e32 v190, 0, v90
	v_mul_u32_u24_e32 v4, 0x110, v91
	v_lshl_add_u64 v[112:113], s[14:15], 0, v[98:99]
	v_lshl_add_u64 v[114:115], s[12:13], 0, v[98:99]
	v_add_u32_e32 v193, 0, v3
	v_mul_u32_u24_e32 v6, 0x90, v88
	v_add3_u32 v195, s0, v2, v94
	v_lshlrev_b32_e32 v98, 4, v97
	v_lshl_add_u64 v[2:3], s[6:7], 0, v[94:95]
	s_mov_b64 s[2:3], 0x4000040
	v_lshlrev_b32_e32 v120, 1, v0
	v_mbcnt_lo_u32_b32 v0, -1, 0
	v_readlane_b32 s86, v236, 0
	v_mov_b32_e32 v89, v99
	v_add_u32_e32 v100, 64, v88
	v_mov_b32_e32 v101, v99
	v_or_b32_e32 v102, 0x80, v88
	v_mov_b32_e32 v103, v99
	v_add_u32_e32 v104, 0xc0, v88
	v_mov_b32_e32 v105, v99
	s_mov_b32 s1, 0
	s_mov_b32 s28, 0x11000
	v_add_u32_e32 v191, 0xd800, v93
	v_or_b32_e32 v192, v94, v185
	v_lshl_add_u32 v194, v1, 1, 0
	v_lshl_add_u64 v[116:117], s[8:9], 0, v[98:99]
	v_lshl_add_u64 v[118:119], v[2:3], 0, s[2:3]
	s_movk_i32 s12, 0x4400
	v_lshlrev_b32_e32 v98, 1, v96
	s_movk_i32 s29, 0x4000
	s_mov_b32 s30, 0x9000
	s_mov_b32 s31, 0xd000
	s_mov_b32 s34, 0x15000
	s_mov_b32 s35, 0x1a000
	s_mov_b32 s36, 0x1e000
	s_mov_b32 s37, 0x22000
	s_mov_b32 s38, 0x26000
	s_mov_b32 s33, 0x2b000
	s_mov_b32 s91, 0x2f000
	s_mov_b32 s92, 0x33000
	s_mov_b32 s93, 0x37000
	s_mov_b32 s94, 0xffff
	s_mov_b32 s95, 0xffff0000
	v_add_u32_e32 v95, v190, v4
	v_mov_b32_e32 v196, 0x358637bd
	s_mov_b32 s90, 0xf800000
	v_mov_b32_e32 v197, 0x260
	s_mov_b32 s87, 0x3e000000
	v_add_u32_e32 v198, v5, v6
	v_mbcnt_hi_u32_b32 v199, -1, v0
	v_mov_b32_e32 v200, 0xffffff80
	v_mov_b32_e32 v201, 0xff800000
	s_mov_b32 s39, s86
	v_readlane_b32 s16, v236, 27
	v_readlane_b32 s17, v236, 28
	v_readlane_b32 s18, v236, 29
	v_readlane_b32 s19, v236, 30
	v_readlane_b32 s20, v236, 31
	v_readlane_b32 s21, v236, 32
	v_readlane_b32 s22, v236, 33
	v_readlane_b32 s23, v236, 34
	v_readlane_b32 s24, v236, 35
	v_readlane_b32 s25, v236, 36
	v_readlane_b32 s26, v236, 37
	v_readlane_b32 s27, v236, 38
	s_branch .LBB0_393

; __device__ __forceinline__ unsigned xb_ld(unsigned* p)              { return __hip_atomic_load(p, __ATOMIC_RELAXED, __HIP_MEMORY_SCOPE_AGENT); }
; __device__ __forceinline__ unsigned xb_add(unsigned* p, unsigned v) { return __hip_atomic_fetch_add(p, v, __ATOMIC_RELAXED, __HIP_MEMORY_SCOPE_AGENT); }
; #define XB_SPIN(cond, bar) do { unsigned _sp = 0; while (cond) { __builtin_amdgcn_s_sleep(1); \
;     if ((++_sp & 255u) == 0u) { if (xb_ld(&(bar)[XB_TMO])) break; if (_sp > XB_SPIN_CAP) { atomicAdd(&(bar)[XB_TMO], 1u); break; } } } } while (0)
; __device__ __forceinline__ void xcd_barrier(const XcdBarrier& b) {
;     ...
;         const unsigned old = xb_add(&bar[XB_XSUB(b.x)], 1u);
;         const unsigned gen = old / nloc;
;         if (old + 1u == (gen + 1u) * nloc) {
;             __builtin_amdgcn_fence(__ATOMIC_RELEASE, "agent");
;             asm volatile("s_waitcnt vmcnt(0)" ::: "memory");
;             const unsigned og = xb_add(&bar[XB_TOP], 1u);
;             const unsigned tg = og / nx;
;             if (og + 1u == (tg + 1u) * nx) xb_add(&bar[XB_TOPGEN], 1u);
;             else XB_SPIN(xb_ld(&bar[XB_TOPGEN]) == tg, bar);
;             __builtin_amdgcn_fence(__ATOMIC_ACQUIRE, "agent");
;             xb_add(&bar[XB_XGEN(b.x)], 1u);
;             asm volatile("s_waitcnt vmcnt(0)" ::: "memory");
;         } else {
;             XB_SPIN(xb_ld(&bar[XB_XGEN(b.x)]) == gen, bar);
;             __builtin_amdgcn_fence(__ATOMIC_ACQUIRE, "agent");
.LBB0_451:
	s_andn2_saveexec_b64 s[4:5], s[4:5]
	s_cbranch_execz .LBB0_471
	s_mov_b64 s[4:5], exec
	v_readfirstlane_b32 s98, v238
	s_cmp_eq_u32 s98, 0
	s_cbranch_scc0 .Lfullbar_3ab
	buffer_inv sc1
	s_branch .LBB0_468
.Lfullbar_3ab:
	buffer_wbl2 sc1
	buffer_inv sc1
	s_waitcnt lgkmcnt(0)
	s_waitcnt vmcnt(0)
	v_mbcnt_lo_u32_b32 v1, s4, 0
	v_mbcnt_hi_u32_b32 v1, s5, v1
	v_cmp_eq_u32_e32 vcc, 0, v1
	s_and_saveexec_b64 s[6:7], vcc
	s_cbranch_execz .LBB0_454
	s_bcnt1_i32_b64 s4, s[4:5]
	v_mov_b32_e32 v2, 0x83000
	v_mov_b32_e32 v3, s4
	global_atomic_add v2, v2, v3, s[48:49] offset:1024 sc0

; #define LAS __attribute__((address_space(3)))
; template <bool FULL>
; __device__ __forceinline__ void hgrn_seg(int b, int h, int sg, const bf16_t* P, const float* LOGF, const float* __restrict__ ogain, bf16_t* OA, float* SSEG, float* DSEG, LAS unsigned char* lds, int tid) {
;     const int lane = tid & 63, wid = __builtin_amdgcn_readfirstlane(tid >> 6), fr = lane & 15, fq = lane >> 4;
;     LAS bf16_t* Qd = (LAS bf16_t*)lds;
;     LAS bf16_t* Kd = Qd + 64 * 136;
;     LAS bf16_t* Qb = Kd + 64 * 136;
;     LAS bf16_t* KlT = Qb + 64 * 136;
;     LAS bf16_t* VT = KlT + 128 * 72;
;     LAS bf16_t* Pm = VT + 128 * 72;
;     LAS bf16_t* ST = Pm + 64 * 72;
;     LAS float* segtot = (LAS float*)(ST + 128 * 136);
;     LAS float* dec = segtot + 1024;
;     LAS float* rsq = dec + 128;
;     const int unit = (b * 8 + h) * 8 + sg;
;     f32x4 sacc[8];
; #pragma unroll
;     for (int kt = 0; kt < 8; ++kt) sacc[kt] = (f32x4){0.f, 0.f, 0.f, 0.f};
;     const int kp = lane, t0 = wid * 8;
;     const int tt = wid & 3, vh = wid >> 2;
; __global__ void __launch_bounds__(NTHR, 2) fwd_megakernel(Args a) {
;     ...
;     for (int u = blk; u < 256; u += G) { const int us = 256 + u;
;         hgrn_seg<true>(u >> 6, (u >> 3) & 7, u & 7, P, LOGF, ogain, OAB + (size_t)M * 1024, SSEG, DSEG, lds, tid);
;         SwaRaw R; swa_load(R, us >> 7, (us >> 5) & 3, us & 31, P, tid);
;         swa_compute(R, us >> 7, (us >> 5) & 3, us & 31, P, qg, kg, sinks, OAB, lds, tid); }
.LBB0_471:
	s_or_b64 exec, exec, s[0:1]
	v_readlane_b32 s0, v235, 1
	v_readlane_b32 s1, v235, 2
	s_and_b64 vcc, exec, s[0:1]
	s_waitcnt lgkmcnt(0)
	s_barrier
	s_cbranch_vccnz .LBB0_501
	v_readlane_b32 s4, v236, 7
	v_readlane_b32 s5, v236, 8
	v_readlane_b32 s6, v236, 9
	v_readlane_b32 s7, v236, 10
	v_readlane_b32 s8, v236, 11
	v_readlane_b32 s9, v236, 12
	v_readlane_b32 s10, v236, 13
	v_readlane_b32 s11, v236, 14
	v_readlane_b32 s4, v236, 56
	v_readlane_b32 s5, v236, 57
	s_movk_i32 s3, 0x1ff
	v_cmp_lt_u32_e64 s[4:5], s3, v186
	v_lshrrev_b32_e32 v0, 4, v160
	s_add_i32 s2, 0, 0x18000
	v_mul_u32_u24_e32 v3, 0x90, v160
	v_writelane_b32 v235, s4, 9
	v_lshlrev_b32_e32 v93, 2, v0
	v_lshl_add_u32 v154, v0, 3, s2
	v_and_b32_e32 v0, 48, v160
	v_mov_b32_e32 v1, 0
	v_readlane_b32 s12, v236, 15
	v_readlane_b32 s13, v236, 16
	v_readlane_b32 s14, v236, 17
	v_readlane_b32 s15, v236, 18
	v_readlane_b32 s16, v236, 19
	v_readlane_b32 s17, v236, 20
	v_readlane_b32 s18, v236, 21
	v_readlane_b32 s19, v236, 22
	v_writelane_b32 v235, s5, 10
	v_lshlrev_b32_e32 v3, 1, v3
	s_add_i32 s4, 0, 0x11400
	v_lshl_add_u64 v[86:87], s[18:19], 0, v[0:1]
	v_and_b32_e32 v2, 56, v188
	v_readlane_b32 s12, v236, 23
	v_add_u32_e32 v167, s4, v3
	v_add_u32_e32 v168, s4, v0
	s_add_i32 s4, 0, 0x15c00
	v_readlane_b32 s8, v236, 60
	v_readlane_b32 s9, v236, 61
	v_add_u32_e32 v157, 0, v0
	v_lshlrev_b32_e32 v4, 2, v2
	v_mov_b32_e32 v5, v1
	v_readlane_b32 s13, v236, 24
	v_readlane_b32 s14, v236, 25
	v_readlane_b32 s15, v236, 26
	v_add_u32_e32 v169, s4, v0
	v_add_u32_e32 v170, s2, v0
	v_lshlrev_b32_e32 v0, 2, v160
	v_lshl_add_u64 v[108:109], s[14:15], 0, v[4:5]
	v_lshl_add_u64 v[110:111], s[12:13], 0, v[4:5]
	v_mul_u32_u24_e32 v4, 0x150, v91
	s_add_i32 s3, 0, 0x16800
	v_and_b32_e32 v5, 24, v188
	v_lshl_add_u64 v[112:113], s[8:9], 0, v[0:1]
	v_lshrrev_b32_e32 v0, 1, v90
	v_readlane_b32 s6, v236, 58
	v_readlane_b32 s7, v236, 59
	v_add_u32_e32 v165, 0, v5
	v_add3_u32 v171, s3, v4, v94
	v_lshl_add_u64 v[4:5], s[8:9], 0, v[0:1]
	s_mov_b64 s[2:3], 0xb801040
	v_mov_b32_e32 v95, v1
	v_lshl_add_u64 v[114:115], v[4:5], 0, s[2:3]
	v_lshl_add_u64 v[4:5], s[6:7], 0, v[94:95]
	s_mov_b64 s[2:3], 0x4000040
	v_writelane_b32 v235, s4, 5
	v_lshl_add_u64 v[118:119], v[4:5], 0, s[2:3]
	s_add_i32 s2, 0, 0x21a00
	v_lshlrev_b32_e32 v98, 3, v160
	v_mov_b32_e32 v99, v1
	s_add_i32 s0, 0, 0x20800
	s_movk_i32 s59, 0x90
	v_lshl_add_u32 v6, v2, 1, 0
	v_mul_u32_u24_e32 v7, 0x48, v88
	v_lshlrev_b32_e32 v0, 4, v97
	v_writelane_b32 v235, s2, 1
	v_lshl_add_u64 v[100:101], s[6:7], 0, v[98:99]
	v_add_u32_e32 v99, s0, v98
	s_add_i32 s0, 0, 0x21800
	v_mad_u32_u24 v158, v91, s59, v157
	v_lshl_add_u32 v162, v7, 1, v6
	v_mul_u32_u24_e32 v7, 0x90, v88
	v_lshl_add_u64 v[116:117], s[8:9], 0, v[0:1]
	v_mbcnt_lo_u32_b32 v0, -1, 0
	v_readlane_b32 s92, v236, 0
	s_mov_b32 s97, 0
	v_lshl_add_u32 v155, v160, 2, 0
	v_add_u32_e32 v156, s0, v98
	v_cmp_gt_u32_e64 s[0:1], 16, v160
	v_add_u32_e32 v159, 0xcc00, v158
	v_mov_b32_e32 v89, v1
	v_add_u32_e32 v102, 64, v88
	v_mov_b32_e32 v103, v1
	v_or_b32_e32 v104, 0x80, v88
	v_mov_b32_e32 v105, v1
	v_add_u32_e32 v106, 0xc0, v88
	v_mov_b32_e32 v107, v1
	v_add_u32_e32 v163, 0xd800, v162
	v_or_b32_e32 v164, v94, v185
	v_add_u32_e32 v166, 0, v3
	s_movk_i32 s58, 0x4400
	v_lshlrev_b32_e32 v96, 1, v96
	s_mov_b32 s33, 0xffff0000
	s_mov_b32 s90, 0xffff
	v_mov_b32_e32 v95, 0x358637bd
	s_mov_b32 s91, 0xf800000
	v_mov_b32_e32 v172, 0x260
	v_lshlrev_b32_e32 v120, 1, v2
	s_mov_b32 s93, 0x3e000000
	v_add_u32_e32 v173, v6, v7
	v_mov_b32_e32 v174, 0x4400
	v_mbcnt_hi_u32_b32 v175, -1, v0
	v_mov_b32_e32 v176, 0xffffff80
	v_mov_b32_e32 v177, 0xff800000
	s_mov_b32 s94, s92
	s_mov_b32 s95, s92
	v_readlane_b32 s10, v236, 62
	v_readlane_b32 s11, v236, 63
	v_readlane_b32 s16, v236, 27
	v_readlane_b32 s17, v236, 28
	v_readlane_b32 s18, v236, 29
	v_readlane_b32 s19, v236, 30
	v_readlane_b32 s20, v236, 31
	v_readlane_b32 s21, v236, 32
	v_readlane_b32 s22, v236, 33
	v_readlane_b32 s23, v236, 34
	v_readlane_b32 s24, v236, 35
	v_readlane_b32 s25, v236, 36
	v_readlane_b32 s26, v236, 37
	v_readlane_b32 s27, v236, 38
	s_branch .LBB0_474
